# touch-prefetch (LDS-DMA to scratch LDS line) of residual rows and LN-stats rows at the top of all four GEMM epilogues
# speedup vs baseline: 1.0314x; 1.0086x over previous
; __device__ __forceinline__ void row_stats(const float* st, int row, int fq, float& mu, float& rs) {
;     const f32x4 a = *(const f32x4*)(st + (size_t)row * 32 + fq * 8), b = *(const f32x4*)(st + (size_t)row * 32 + fq * 8 + 4);
;     float s = (a[0] + a[2]) + (b[0] + b[2]), q = (a[1] + a[3]) + (b[1] + b[3]);
;     s += __shfl_xor(s, 16); s += __shfl_xor(s, 32); q += __shfl_xor(q, 16); q += __shfl_xor(q, 32);
;     mu = s * (1.0f / 1024.0f); const float var = fmaxf(q * (1.0f / 1024.0f) - mu * mu, 0.f); rs = rsqrtf(var + LN_EPS);
; }
;     __device__ __forceinline__ void operator()(const f32x4 (&acc)[2][2][4][2], const Unit& u, int wr, int wc, int fr_, int fq_) const {
;     ...
;             float mus[4], rss[4];
; #pragma unroll
;             for (int q = 0; q < 4; ++q) { mus[q] = 0.f; rss[q] = 1.f; if (st) row_stats(st, u.pm * 256 + ai * 128 + q * 16 + wr * 64 + fr, fq, mus[q], rss[q]); }
;             asm volatile("" ::: "memory");
.LBB0_227:
	s_lshl_b32 s51, s42, 8
	v_readlane_b32 s14, v255, 12
	s_add_i32 s1, s51, s63
	v_ashrrev_i32_e32 v145, 31, v144
	v_readlane_b32 s15, v255, 13
	v_add_u32_e32 v182, s1, v187
	v_mov_b32_e32 v202, 1.0
	v_lshl_add_u64 v[184:185], v[144:145], 2, s[14:15]
	v_mov_b32_e32 v144, 0
	s_and_b64 vcc, exec, s[48:49]
	v_mov_b32_e32 v200, 1.0
	s_cbranch_vccnz .LBB0_229
	v_ashrrev_i32_e32 v183, 31, v182
	v_lshlrev_b64 v[144:145], 7, v[182:183]
	v_lshl_add_u64 v[164:165], v[184:185], 0, v[144:145]
	s_mov_b32 m0, 0x20000
	v_and_b32_e32 v144, 48, v231
	v_mov_b32_e32 v145, 0
	v_lshlrev_b32_e32 v144, 7, v144
	v_lshl_add_u64 v[146:147], v[164:165], 0, v[144:145]
	global_load_lds_dword v[146:147], off
	v_add_u32_e32 v144, 0x4000, v144
	v_lshl_add_u64 v[146:147], v[164:165], 0, v[144:145]
	global_load_lds_dword v[146:147], off
	global_load_dwordx4 v[144:147], v[164:165], off
	s_nop 0
	global_load_dwordx4 v[164:167], v[164:165], off offset:16
	v_xor_b32_e32 v183, 16, v231
	v_cmp_lt_i32_e32 vcc, v183, v232
	s_waitcnt vmcnt(0)
	v_pk_add_f32 v[144:145], v[144:145], v[146:147]
	v_cndmask_b32_e32 v183, v231, v183, vcc
	v_pk_add_f32 v[146:147], v[164:165], v[166:167]
	v_lshlrev_b32_e32 v183, 2, v183
	v_pk_add_f32 v[144:145], v[144:145], v[146:147]
	ds_bpermute_b32 v146, v183, v144
	ds_bpermute_b32 v147, v183, v145
	v_xor_b32_e32 v164, 32, v231
	v_cmp_lt_i32_e32 vcc, v164, v232
	s_waitcnt lgkmcnt(0)
	v_pk_add_f32 v[144:145], v[144:145], v[146:147]
	v_cndmask_b32_e32 v164, v231, v164, vcc
	v_lshlrev_b32_e32 v164, 2, v164
	ds_bpermute_b32 v146, v164, v144
	ds_bpermute_b32 v147, v164, v145
	s_waitcnt lgkmcnt(0)
	v_pk_add_f32 v[144:145], v[144:145], v[146:147]
	s_nop 0
	v_pk_mul_f32 v[144:145], v[144:145], s[74:75] op_sel_hi:[1,0]
	s_nop 0
	v_fma_f32 v145, -v144, v144, v145
	v_max_f32_e32 v145, 0, v145
	v_add_f32_e32 v145, 0x3727c5ac, v145
	v_mul_f32_e32 v146, 0x4b800000, v145
	v_cmp_gt_f32_e32 vcc, s75, v145
	s_nop 1
	v_cndmask_b32_e32 v145, v145, v146, vcc
	v_rsq_f32_e32 v145, v145
	s_nop 0
	v_mul_f32_e32 v146, 0x45800000, v145
	v_cndmask_b32_e32 v200, v145, v146, vcc

; __device__ __forceinline__ float lo_bf(unsigned x) { return __uint_as_float(x << 16); }
; __device__ __forceinline__ float hi_bf(unsigned x) { return __uint_as_float(x & 0xffff0000u); }
;     __device__ __forceinline__ void operator()(const f32x4 (&acc)[2][2][4][2], const Unit& u, int wr, int wc, int fr_, int fq_) const {
;     ...
;         const int lc = wc * 32 + fq * 8;
;         const float* xb = xrow_ptr(xp, xs, grow0 + (size_t)u.pm * 256) - (size_t)u.pm * 256 * 1024;
;         f32x4 gv[2][2], bv[2][2];
; #pragma unroll
;         for (int bj = 0; bj < 2; ++bj)
; #pragma unroll
;             for (int n = 0; n < 2; ++n) { const int col = u.pn * 256 + bj * 128 + lc + 4 * n;
;                 if (st2) { gv[bj][n] = *(const f32x4*)(g2 + col); bv[bj][n] = *(const f32x4*)(b2 + col); } else { gv[bj][n] = (f32x4){1.f, 1.f, 1.f, 1.f}; bv[bj][n] = (f32x4){0.f, 0.f, 0.f, 0.f}; } }
; #pragma unroll
;         for (int am = 0; am < 4; ++am) { const int ai = am >> 1, m0 = (am & 1) * 2;
;             f32x4 xr[2][2][2]; float mu[2], rs[2];
; #pragma unroll
;             for (int mm = 0; mm < 2; ++mm) { const int m = mm; const int mg = m0 + mm;
;                 const int grow = u.pm * 256 + ai * 128 + mg * 16 + wr * 64 + fr;
; #pragma unroll
;                 for (int bj = 0; bj < 2; ++bj) { const size_t off = (size_t)grow * 1024 + u.pn * 256 + bj * 128 + lc;
;                     if (st2) { const u32x4 w = *(const u32x4*)(xres + off);
;                         xr[m][bj][0] = (f32x4){lo_bf(w.x), hi_bf(w.x), lo_bf(w.y), hi_bf(w.y)}; xr[m][bj][1] = (f32x4){lo_bf(w.z), hi_bf(w.z), lo_bf(w.w), hi_bf(w.w)}; }
;                     else { xr[m][bj][0] = *(const f32x4*)(xb + off); xr[m][bj][1] = *(const f32x4*)(xb + off + 4); } }
.LBB0_718:
	s_ashr_i32 s11, s10, 31
	s_lshl_b64 s[14:15], s[10:11], 8
	v_readlane_b32 s16, v255, 2
	v_readlane_b32 s17, v255, 3
	s_add_u32 s14, s14, s16
	s_addc_u32 s15, s15, s17
	v_readlane_b32 s76, v254, 43
	s_lshl_b64 s[16:17], s[14:15], 12
	v_readlane_b32 s78, v254, 45
	v_readlane_b32 s79, v254, 46
	s_add_u32 s1, s78, s16
	s_addc_u32 s18, s79, s17
	s_add_u32 s1, s1, 0xf0000000
	s_addc_u32 s44, s18, -1
	s_lshl_b64 s[18:19], s[10:11], 20
	s_sub_u32 s11, 0, s18
	s_subb_u32 s18, 0, s19
	v_readlane_b32 s77, v254, 44
	v_mov_b64_e32 v[62:63], 0x10000
	s_add_u32 s16, s76, s16
	v_cmp_lt_u64_e32 vcc, s[14:15], v[62:63]
	s_addc_u32 s17, s77, s17
	s_and_b64 s[14:15], vcc, exec
	s_cselect_b32 s1, s16, s1
	s_cselect_b32 s14, s17, s44
	s_add_u32 s56, s1, s11
	s_addc_u32 s57, s14, s18
	s_lshl_b32 s1, s10, 8
	s_add_i32 s1, s1, s39
	v_add_u32_e32 v214, s1, v159
	s_ashr_i32 s53, s52, 31
	v_ashrrev_i32_e32 v209, 31, v208
	v_ashrrev_i32_e32 v215, 31, v214
	v_lshl_add_u64 v[216:217], v[208:209], 0, s[52:53]
	v_lshlrev_b64 v[62:63], 10, v[214:215]
	v_lshl_add_u64 v[160:161], v[216:217], 0, v[62:63]
	v_readlane_b32 s82, v254, 49
	v_readlane_b32 s83, v254, 50
	v_readlane_b32 s84, v254, 51
	v_readlane_b32 s85, v254, 52
	v_readlane_b32 s86, v254, 53
	v_readlane_b32 s87, v254, 54
	v_readlane_b32 s88, v254, 55
	v_readlane_b32 s89, v254, 56
	s_mov_b64 s[10:11], -1
	s_and_b64 vcc, exec, s[42:43]
	s_mov_b32 m0, 0x20000
	v_and_b32_e32 v162, 48, v231
	v_mov_b32_e32 v163, 0
	s_and_b64 s[98:99], exec, s[42:43]
	s_cbranch_scc0 .Ltouch_out_bf16
	v_lshlrev_b32_e32 v162, 12, v162
	v_lshl_add_u64 v[164:165], v[160:161], 2, s[56:57]
	v_lshl_add_u64 v[186:187], v[164:165], 0, v[162:163]
	global_load_lds_dword v[186:187], off
	global_load_lds_dword v[186:187], off offset:512
	v_add_u32_e32 v162, 0x80000, v162
	v_lshl_add_u64 v[186:187], v[164:165], 0, v[162:163]
	global_load_lds_dword v[186:187], off
	global_load_lds_dword v[186:187], off offset:512
	s_branch .Ltouch_out_done
.Ltouch_out_bf16:
	v_lshlrev_b32_e32 v162, 11, v162
	v_lshl_add_u64 v[164:165], v[160:161], 1, s[6:7]
	v_lshl_add_u64 v[186:187], v[164:165], 0, v[162:163]
	global_load_lds_dword v[186:187], off
	global_load_lds_dword v[186:187], off offset:256
	v_add_u32_e32 v162, 0x40000, v162
	v_lshl_add_u64 v[186:187], v[164:165], 0, v[162:163]
	global_load_lds_dword v[186:187], off
	global_load_lds_dword v[186:187], off offset:256
.Ltouch_out_done:
	v_lshl_add_u64 v[62:63], v[160:161], 1, s[6:7]
	v_readlane_b32 s80, v254, 47
	v_readlane_b32 s81, v254, 48
	v_readlane_b32 s90, v254, 57
	v_readlane_b32 s91, v254, 58
	s_cbranch_vccnz .LBB0_720
	global_load_dwordx4 v[162:165], v[62:63], off
	s_waitcnt vmcnt(0)
	v_lshlrev_b32_e32 v186, 16, v162
	v_and_b32_e32 v187, 0xffff0000, v162
	v_lshlrev_b32_e32 v188, 16, v163
	v_and_b32_e32 v189, 0xffff0000, v163
	v_lshlrev_b32_e32 v182, 16, v164
	v_and_b32_e32 v183, 0xffff0000, v164
	v_lshlrev_b32_e32 v184, 16, v165
	v_and_b32_e32 v185, 0xffff0000, v165
	v_lshl_add_u64 v[160:161], v[160:161], 2, s[56:57]
	s_cbranch_execnz .LBB0_722
	s_branch .LBB0_721

; __device__ __forceinline__ float lo_bf(unsigned x) { return __uint_as_float(x << 16); }
; __device__ __forceinline__ float hi_bf(unsigned x) { return __uint_as_float(x & 0xffff0000u); }
; __device__ __forceinline__ void row_stats(const float* st, int row, int fq, float& mu, float& rs) {
;     const f32x4 a = *(const f32x4*)(st + (size_t)row * 32 + fq * 8), b = *(const f32x4*)(st + (size_t)row * 32 + fq * 8 + 4);
;     float s = (a[0] + a[2]) + (b[0] + b[2]), q = (a[1] + a[3]) + (b[1] + b[3]);
;     s += __shfl_xor(s, 16); s += __shfl_xor(s, 32); q += __shfl_xor(q, 16); q += __shfl_xor(q, 32);
;     mu = s * (1.0f / 1024.0f); const float var = fmaxf(q * (1.0f / 1024.0f) - mu * mu, 0.f); rs = rsqrtf(var + LN_EPS);
; }
;     __device__ __forceinline__ void operator()(const f32x4 (&acc)[2][2][4][2], const Unit& u, int wr, int wc, int fr_, int fq_) const {
;     ...
;                     if (st2) { const u32x4 w = *(const u32x4*)(xres + off);
;                         xr[m][bj][0] = (f32x4){lo_bf(w.x), hi_bf(w.x), lo_bf(w.y), hi_bf(w.y)}; xr[m][bj][1] = (f32x4){lo_bf(w.z), hi_bf(w.z), lo_bf(w.w), hi_bf(w.w)}; }
;                     else { xr[m][bj][0] = *(const f32x4*)(xb + off); xr[m][bj][1] = *(const f32x4*)(xb + off + 4); } }
;                 mu[m] = 0.f; rs[m] = 1.f; if (st2) row_stats(st2, grow, fq, mu[m], rs[m]);
;             }
.LBB0_726:
	v_readlane_b32 s10, v255, 12
	v_ashrrev_i32_e32 v159, 31, v158
	v_readlane_b32 s11, v255, 13
	s_and_b64 vcc, exec, s[42:43]
	v_lshlrev_b64 v[220:221], 7, v[214:215]
	v_lshl_add_u64 v[218:219], v[158:159], 2, s[10:11]
	s_cbranch_vccnz .LBB0_728
	v_lshl_add_u64 v[62:63], v[218:219], 0, v[220:221]
	v_and_b32_e32 v166, 48, v231
	v_mov_b32_e32 v167, 0
	v_lshlrev_b32_e32 v166, 7, v166
	v_lshl_add_u64 v[224:225], v[62:63], 0, v[166:167]
	global_load_lds_dword v[224:225], off
	v_add_u32_e32 v166, 0x4000, v166
	v_lshl_add_u64 v[224:225], v[62:63], 0, v[166:167]
	global_load_lds_dword v[224:225], off
	global_load_dwordx4 v[158:161], v[62:63], off
	global_load_dwordx4 v[162:165], v[62:63], off offset:16
	v_xor_b32_e32 v62, 16, v231
	v_cmp_lt_i32_e32 vcc, v62, v232
	s_nop 1
	v_cndmask_b32_e32 v62, v231, v62, vcc
	v_lshlrev_b32_e32 v166, 2, v62
	s_waitcnt vmcnt(0)
	v_pk_add_f32 v[62:63], v[158:159], v[160:161]
	v_pk_add_f32 v[158:159], v[162:163], v[164:165]
	v_xor_b32_e32 v160, 32, v231
	v_pk_add_f32 v[62:63], v[62:63], v[158:159]
	ds_bpermute_b32 v158, v166, v62
	ds_bpermute_b32 v159, v166, v63
	v_cmp_lt_i32_e32 vcc, v160, v232
	s_waitcnt lgkmcnt(0)
	v_pk_add_f32 v[62:63], v[62:63], v[158:159]
	v_cndmask_b32_e32 v160, v231, v160, vcc
	v_lshlrev_b32_e32 v160, 2, v160
	ds_bpermute_b32 v158, v160, v62
	ds_bpermute_b32 v159, v160, v63
	s_waitcnt lgkmcnt(0)
	v_pk_add_f32 v[62:63], v[62:63], v[158:159]
	s_nop 0
	v_pk_mul_f32 v[226:227], v[62:63], s[74:75] op_sel_hi:[1,0]
	s_nop 0
	v_fma_f32 v62, -v226, v226, v227
	v_max_f32_e32 v62, 0, v62
	v_add_f32_e32 v62, 0x3727c5ac, v62
	v_mul_f32_e32 v63, 0x4b800000, v62
	v_cmp_gt_f32_e32 vcc, s75, v62
	s_nop 1
	v_cndmask_b32_e32 v62, v62, v63, vcc
	v_rsq_f32_e32 v62, v62
	s_nop 0
	v_mul_f32_e32 v63, 0x45800000, v62
	v_cndmask_b32_e32 v192, v62, v63, vcc
	s_branch .LBB0_729

; #define PG8_STAGE(bufoff, gbase, voff) do { _Pragma("unroll") for (int _i = 0; _i < 2; ++_i) \
;         __builtin_amdgcn_global_load_lds((const unsigned*)((const char*)(gbase) + (voff)[_i]), (LAS unsigned*)(lds + (bufoff) + ldsw + _i * 8192), 16, 0, 0); } while (0)
; #define PG8_LDA(dst, b, h) do { _Pragma("unroll") for (int m = 0; m < 4; ++m) _Pragma("unroll") for (int k = 0; k < 2; ++k) dst[m][k] = *(const LAS bf16x8*)(lds + PG8_SA(b, h) + aoff + m * 2048 + k * 1024); } while (0)
; #define PG8_WAIT_V(n) asm volatile("s_waitcnt vmcnt(" #n ")" ::: "memory")
; #define PG8_WAIT_L(n) asm volatile("s_waitcnt lgkmcnt(" #n ")" ::: "memory")
; template <class Epi>
; __device__ __forceinline__ void gemm_phase(LAS unsigned char* lds, const Gemm g, const StaticOrder& S, const Epi& E) {
;     ...
;         for (int t = 0; t < nt; t += 2) {
;             const bool last = (t == nt - 2);
;             const char* a1 = cA + (size_t)(t + 1) * kstep;
;             const char* a2 = last ? nA : cA + (size_t)(t + 2) * kstep; const char* b2 = last ? nB : cB + (size_t)(t + 2) * kstep;
;             const char* a3 = a2 + kstep; const char* b3 = b2 + kstep;
;             PG8_LDB(B0, 0, 0); PG8_SCHED; PG8_LDA(At, 0, 0); PG8_STAGE(PG8_SA(1, 1), a1 + hstep, voffA);
;             PG8_WAIT_L(8); PG8_BAR; PG8_WAIT_L(0); PG8_MMA(0, 0, At, B0); PG8_BAR; PG8_SCHED;
;             PG8_LDB(B1, 0, 1); PG8_STAGE(PG8_SB(0, 0), b2, voffB);
;             PG8_BAR; PG8_WAIT_L(0); PG8_MMA(0, 1, At, B1); PG8_BAR;
;             PG8_LDA(At, 0, 1); PG8_STAGE(PG8_SA(0, 0), a2, voffA);
;             PG8_BAR; PG8_WAIT_L(0); PG8_MMA(1, 0, At, B0); PG8_BAR; PG8_SCHED;
;             PG8_STAGE(PG8_SB(0, 1), b2 + hstep, voffB);
;             PG8_WAIT_V(6); PG8_BAR; PG8_MMA(1, 1, At, B1); PG8_BAR;
;             PG8_LDB(B0, 1, 0); PG8_SCHED; PG8_LDA(At, 1, 0); PG8_STAGE(PG8_SA(0, 1), a2 + hstep, voffA);
;             PG8_WAIT_L(8); PG8_BAR; PG8_WAIT_L(0); PG8_MMA(0, 0, At, B0); PG8_BAR; PG8_SCHED;
;             PG8_LDB(B1, 1, 1); PG8_STAGE(PG8_SB(1, 0), b3, voffB);
;             PG8_BAR; PG8_WAIT_L(0); PG8_MMA(0, 1, At, B1); PG8_BAR;
;             PG8_LDA(At, 1, 1); PG8_STAGE(PG8_SA(1, 0), a3, voffA);
;             PG8_BAR; PG8_WAIT_L(0); PG8_MMA(1, 0, At, B0); PG8_BAR; PG8_SCHED;
;             PG8_STAGE(PG8_SB(1, 1), b3 + hstep, voffB);
;             PG8_WAIT_V(6); PG8_BAR; PG8_MMA(1, 1, At, B1); PG8_BAR;
.LBB0_947:
	s_add_u32 s0, s10, 0x100
	s_addc_u32 s1, s11, 0
	s_add_i32 s61, 0, 0x10000
	v_add_u32_e32 v36, s61, v220
	ds_read_b128 v[24:27], v36
	ds_read_b128 v[28:31], v36 offset:1024
	ds_read_b128 v[32:35], v36 offset:2048
	ds_read_b128 v[36:39], v36 offset:3072
	s_cmp_eq_u32 s53, 40
	s_cselect_b32 s17, s49, s1
	s_cselect_b32 s16, s48, s0
	s_cselect_b32 s15, s43, s52
	s_cselect_b32 s14, s42, s50
	v_lshl_add_u64 v[186:187], s[10:11], 0, v[182:183]
	s_add_i32 m0, s26, 0xc000
	ds_read_b128 v[40:43], v221
	ds_read_b128 v[44:47], v221 offset:1024
	ds_read_b128 v[48:51], v221 offset:2048
	ds_read_b128 v[52:55], v221 offset:3072
	ds_read_b128 v[160:163], v221 offset:4096
	ds_read_b128 v[164:167], v221 offset:5120
	ds_read_b128 v[168:171], v221 offset:6144
	ds_read_b128 v[172:175], v221 offset:7168
	global_load_lds_dwordx4 v[186:187], off
	v_lshl_add_u64 v[186:187], s[10:11], 0, v[184:185]
	s_add_i32 m0, s26, 0xe000
	s_nop 0
	global_load_lds_dwordx4 v[186:187], off
	s_waitcnt lgkmcnt(8)
	s_barrier
	s_waitcnt lgkmcnt(0)
	s_setprio 1
	s_waitcnt lgkmcnt(0)
	v_mfma_f32_16x16x32_bf16 v[156:159], v[24:27], v[40:43], v[156:159]
	v_mfma_f32_16x16x32_bf16 v[152:155], v[32:35], v[40:43], v[152:155]
	v_mfma_f32_16x16x32_bf16 v[140:143], v[24:27], v[48:51], v[140:143]
	v_mfma_f32_16x16x32_bf16 v[136:139], v[32:35], v[48:51], v[136:139]
	v_mfma_f32_16x16x32_bf16 v[124:127], v[24:27], v[160:163], v[124:127]
	v_mfma_f32_16x16x32_bf16 v[120:123], v[32:35], v[160:163], v[120:123]
	v_mfma_f32_16x16x32_bf16 v[108:111], v[24:27], v[168:171], v[108:111]
	v_mfma_f32_16x16x32_bf16 v[104:107], v[32:35], v[168:171], v[104:107]
	v_mfma_f32_16x16x32_bf16 v[156:159], v[28:31], v[44:47], v[156:159]
	v_mfma_f32_16x16x32_bf16 v[152:155], v[36:39], v[44:47], v[152:155]
	v_mfma_f32_16x16x32_bf16 v[140:143], v[28:31], v[52:55], v[140:143]
	v_mfma_f32_16x16x32_bf16 v[136:139], v[36:39], v[52:55], v[136:139]
	v_mfma_f32_16x16x32_bf16 v[124:127], v[28:31], v[164:167], v[124:127]
	v_mfma_f32_16x16x32_bf16 v[120:123], v[36:39], v[164:167], v[120:123]
	v_mfma_f32_16x16x32_bf16 v[108:111], v[28:31], v[172:175], v[108:111]
	v_mfma_f32_16x16x32_bf16 v[104:107], v[36:39], v[172:175], v[104:107]
	s_setprio 0
	s_barrier
	s_add_i32 s62, 0, 0x14000
	s_add_i32 s10, s61, s21
	v_add_u32_e32 v192, s62, v220
	v_lshl_add_u64 v[214:215], s[14:15], 0, v[190:191]
	s_mov_b32 m0, s10
	ds_read_b128 v[186:189], v192
	ds_read_b128 v[194:197], v192 offset:1024
	ds_read_b128 v[198:201], v192 offset:2048
	ds_read_b128 v[202:205], v192 offset:3072
	global_load_lds_dwordx4 v[214:215], off
	v_lshl_add_u64 v[216:217], s[14:15], 0, v[176:177]
	s_add_i32 m0, s10, 0x2000
	s_nop 0
	global_load_lds_dwordx4 v[216:217], off
	s_barrier
	s_waitcnt lgkmcnt(0)
	s_setprio 1
	s_waitcnt lgkmcnt(0)
	v_mfma_f32_16x16x32_bf16 v[148:151], v[186:189], v[40:43], v[148:151]
	v_mfma_f32_16x16x32_bf16 v[40:43], v[198:201], v[40:43], v[144:147]
	v_mfma_f32_16x16x32_bf16 v[148:151], v[194:197], v[44:47], v[148:151]
	v_mfma_f32_16x16x32_bf16 v[40:43], v[202:205], v[44:47], v[40:43]
	v_mfma_f32_16x16x32_bf16 v[44:47], v[186:189], v[48:51], v[132:135]
	v_mfma_f32_16x16x32_bf16 v[48:51], v[198:201], v[48:51], v[128:131]
	v_mfma_f32_16x16x32_bf16 v[112:115], v[198:201], v[160:163], v[112:115]
	v_mfma_f32_16x16x32_bf16 v[100:103], v[186:189], v[168:171], v[100:103]
	v_mfma_f32_16x16x32_bf16 v[96:99], v[198:201], v[168:171], v[96:99]
	v_mfma_f32_16x16x32_bf16 v[44:47], v[194:197], v[52:55], v[44:47]
	v_mfma_f32_16x16x32_bf16 v[48:51], v[202:205], v[52:55], v[48:51]
	v_mfma_f32_16x16x32_bf16 v[52:55], v[186:189], v[160:163], v[116:119]
	v_mfma_f32_16x16x32_bf16 v[112:115], v[202:205], v[164:167], v[112:115]
	v_mfma_f32_16x16x32_bf16 v[100:103], v[194:197], v[172:175], v[100:103]
	v_mfma_f32_16x16x32_bf16 v[96:99], v[202:205], v[172:175], v[96:99]
	v_mfma_f32_16x16x32_bf16 v[52:55], v[194:197], v[164:167], v[52:55]
	s_setprio 0
	s_mov_b32 m0, s26
	v_lshl_add_u64 v[222:223], s[16:17], 0, v[180:181]
	s_barrier
	ds_read_b128 v[116:119], v221 offset:16384
	ds_read_b128 v[128:131], v221 offset:17408
	ds_read_b128 v[132:135], v221 offset:18432
	ds_read_b128 v[144:147], v221 offset:19456
	ds_read_b128 v[160:163], v221 offset:20480
	ds_read_b128 v[164:167], v221 offset:21504
	ds_read_b128 v[168:171], v221 offset:22528
	ds_read_b128 v[172:175], v221 offset:23552
	global_load_lds_dwordx4 v[222:223], off
	v_lshl_add_u64 v[224:225], s[16:17], 0, v[178:179]
	s_mov_b32 m0, s27
	s_nop 0
	global_load_lds_dwordx4 v[224:225], off
	s_barrier
	s_waitcnt lgkmcnt(0)
	s_setprio 1
	s_waitcnt lgkmcnt(0)
	v_mfma_f32_16x16x32_bf16 v[92:95], v[24:27], v[116:119], v[92:95]
	v_mfma_f32_16x16x32_bf16 v[88:91], v[32:35], v[116:119], v[88:91]
	v_mfma_f32_16x16x32_bf16 v[76:79], v[24:27], v[132:135], v[76:79]
	v_mfma_f32_16x16x32_bf16 v[72:75], v[32:35], v[132:135], v[72:75]
	v_mfma_f32_16x16x32_bf16 v[60:63], v[24:27], v[160:163], v[60:63]
	v_mfma_f32_16x16x32_bf16 v[56:59], v[32:35], v[160:163], v[56:59]
	v_mfma_f32_16x16x32_bf16 v[12:15], v[24:27], v[168:171], v[12:15]
	v_mfma_f32_16x16x32_bf16 v[8:11], v[32:35], v[168:171], v[8:11]
	v_mfma_f32_16x16x32_bf16 v[92:95], v[28:31], v[128:131], v[92:95]
	v_mfma_f32_16x16x32_bf16 v[88:91], v[36:39], v[128:131], v[88:91]
	v_mfma_f32_16x16x32_bf16 v[76:79], v[28:31], v[144:147], v[76:79]
	v_mfma_f32_16x16x32_bf16 v[72:75], v[36:39], v[144:147], v[72:75]
	v_mfma_f32_16x16x32_bf16 v[60:63], v[28:31], v[164:167], v[60:63]
	v_mfma_f32_16x16x32_bf16 v[56:59], v[36:39], v[164:167], v[56:59]
	v_mfma_f32_16x16x32_bf16 v[12:15], v[28:31], v[172:175], v[12:15]
	v_mfma_f32_16x16x32_bf16 v[8:11], v[36:39], v[172:175], v[8:11]
	s_setprio 0
	s_barrier
; #define PG8_STAGE(bufoff, gbase, voff) do { _Pragma("unroll") for (int _i = 0; _i < 2; ++_i) \
;         __builtin_amdgcn_global_load_lds((const unsigned*)((const char*)(gbase) + (voff)[_i]), (LAS unsigned*)(lds + (bufoff) + ldsw + _i * 8192), 16, 0, 0); } while (0)
; #define PG8_LDA(dst, b, h) do { _Pragma("unroll") for (int m = 0; m < 4; ++m) _Pragma("unroll") for (int k = 0; k < 2; ++k) dst[m][k] = *(const LAS bf16x8*)(lds + PG8_SA(b, h) + aoff + m * 2048 + k * 1024); } while (0)
; #define PG8_WAIT_V(n) asm volatile("s_waitcnt vmcnt(" #n ")" ::: "memory")
; #define PG8_WAIT_L(n) asm volatile("s_waitcnt lgkmcnt(" #n ")" ::: "memory")
; template <class Epi>
; __device__ __forceinline__ void gemm_phase(LAS unsigned char* lds, const Gemm g, const StaticOrder& S, const Epi& E) {
;     ...
;         for (int t = 0; t < nt; t += 2) {
;             const bool last = (t == nt - 2);
;             const char* a1 = cA + (size_t)(t + 1) * kstep;
;             const char* a2 = last ? nA : cA + (size_t)(t + 2) * kstep; const char* b2 = last ? nB : cB + (size_t)(t + 2) * kstep;
;             const char* a3 = a2 + kstep; const char* b3 = b2 + kstep;
;             PG8_LDB(B0, 0, 0); PG8_SCHED; PG8_LDA(At, 0, 0); PG8_STAGE(PG8_SA(1, 1), a1 + hstep, voffA);
;             PG8_WAIT_L(8); PG8_BAR; PG8_WAIT_L(0); PG8_MMA(0, 0, At, B0); PG8_BAR; PG8_SCHED;
;             PG8_LDB(B1, 0, 1); PG8_STAGE(PG8_SB(0, 0), b2, voffB);
;             PG8_BAR; PG8_WAIT_L(0); PG8_MMA(0, 1, At, B1); PG8_BAR;
;             PG8_LDA(At, 0, 1); PG8_STAGE(PG8_SA(0, 0), a2, voffA);
;             PG8_BAR; PG8_WAIT_L(0); PG8_MMA(1, 0, At, B0); PG8_BAR; PG8_SCHED;
;             PG8_STAGE(PG8_SB(0, 1), b2 + hstep, voffB);
;             PG8_WAIT_V(6); PG8_BAR; PG8_MMA(1, 1, At, B1); PG8_BAR;
;             PG8_LDB(B0, 1, 0); PG8_SCHED; PG8_LDA(At, 1, 0); PG8_STAGE(PG8_SA(0, 1), a2 + hstep, voffA);
;             PG8_WAIT_L(8); PG8_BAR; PG8_WAIT_L(0); PG8_MMA(0, 0, At, B0); PG8_BAR; PG8_SCHED;
;             PG8_LDB(B1, 1, 1); PG8_STAGE(PG8_SB(1, 0), b3, voffB);
;             PG8_BAR; PG8_WAIT_L(0); PG8_MMA(0, 1, At, B1); PG8_BAR;
;             PG8_LDA(At, 1, 1); PG8_STAGE(PG8_SA(1, 0), a3, voffA);
;             PG8_BAR; PG8_WAIT_L(0); PG8_MMA(1, 0, At, B0); PG8_BAR; PG8_SCHED;
;             PG8_STAGE(PG8_SB(1, 1), b3 + hstep, voffB);
;             PG8_WAIT_V(6); PG8_BAR; PG8_MMA(1, 1, At, B1); PG8_BAR;
	s_add_u32 s10, s14, 0xb0000
	s_addc_u32 s11, s15, 0
	s_add_i32 s61, s62, s21
	v_lshl_add_u64 v[24:25], s[10:11], 0, v[190:191]
	s_mov_b32 m0, s61
	s_nop 0
	global_load_lds_dwordx4 v[24:25], off
	v_lshl_add_u64 v[24:25], s[10:11], 0, v[176:177]
	s_add_i32 m0, s61, 0x2000
	s_nop 0
	global_load_lds_dwordx4 v[24:25], off
	s_waitcnt vmcnt(6)
	s_barrier
	s_setprio 1
	v_mfma_f32_16x16x32_bf16 v[20:23], v[186:189], v[160:163], v[20:23]
	v_mfma_f32_16x16x32_bf16 v[16:19], v[198:201], v[160:163], v[16:19]
	v_mfma_f32_16x16x32_bf16 v[4:7], v[186:189], v[168:171], v[4:7]
	v_mfma_f32_16x16x32_bf16 v[0:3], v[198:201], v[168:171], v[0:3]
	v_mfma_f32_16x16x32_bf16 v[24:27], v[186:189], v[116:119], v[84:87]
	v_mfma_f32_16x16x32_bf16 v[28:31], v[198:201], v[116:119], v[80:83]
	v_mfma_f32_16x16x32_bf16 v[32:35], v[186:189], v[132:135], v[68:71]
	v_mfma_f32_16x16x32_bf16 v[36:39], v[198:201], v[132:135], v[64:67]
	v_mfma_f32_16x16x32_bf16 v[20:23], v[194:197], v[164:167], v[20:23]
	v_mfma_f32_16x16x32_bf16 v[16:19], v[202:205], v[164:167], v[16:19]
	v_mfma_f32_16x16x32_bf16 v[4:7], v[194:197], v[172:175], v[4:7]
	v_mfma_f32_16x16x32_bf16 v[0:3], v[202:205], v[172:175], v[0:3]
	v_mfma_f32_16x16x32_bf16 v[24:27], v[194:197], v[128:131], v[24:27]
	v_mfma_f32_16x16x32_bf16 v[28:31], v[202:205], v[128:131], v[28:31]
	v_mfma_f32_16x16x32_bf16 v[32:35], v[194:197], v[144:147], v[32:35]
	v_mfma_f32_16x16x32_bf16 v[36:39], v[202:205], v[144:147], v[36:39]
	s_setprio 0
	s_add_i32 s61, 0, 0x18000
	v_add_u32_e32 v84, s61, v220
	s_barrier
	ds_read_b128 v[64:67], v84
	ds_read_b128 v[68:71], v84 offset:1024
	ds_read_b128 v[80:83], v84 offset:2048
	ds_read_b128 v[84:87], v84 offset:3072
	s_add_u32 s10, s16, 0xb0000
	s_addc_u32 s11, s17, 0
	s_mov_b32 m0, s30
	v_lshl_add_u64 v[132:133], s[10:11], 0, v[180:181]
	ds_read_b128 v[116:119], v221 offset:32768
	ds_read_b128 v[128:131], v221 offset:33792
	ds_read_b128 v[160:163], v221 offset:34816
	ds_read_b128 v[164:167], v221 offset:35840
	ds_read_b128 v[168:171], v221 offset:36864
	ds_read_b128 v[172:175], v221 offset:37888
	ds_read_b128 v[186:189], v221 offset:38912
	ds_read_b128 v[194:197], v221 offset:39936
	global_load_lds_dwordx4 v[132:133], off
	v_lshl_add_u64 v[132:133], s[10:11], 0, v[178:179]
	s_mov_b32 m0, s31
	s_nop 0
	global_load_lds_dwordx4 v[132:133], off
	s_waitcnt lgkmcnt(8)
	s_barrier
	s_waitcnt lgkmcnt(0)
	s_setprio 1
	s_waitcnt lgkmcnt(0)
	v_mfma_f32_16x16x32_bf16 v[132:135], v[64:67], v[116:119], v[156:159]
	v_mfma_f32_16x16x32_bf16 v[156:159], v[68:71], v[128:131], v[132:135]
	v_mfma_f32_16x16x32_bf16 v[132:135], v[80:83], v[116:119], v[152:155]
	v_mfma_f32_16x16x32_bf16 v[152:155], v[84:87], v[128:131], v[132:135]
	v_mfma_f32_16x16x32_bf16 v[132:135], v[64:67], v[160:163], v[140:143]
	v_mfma_f32_16x16x32_bf16 v[140:143], v[68:71], v[164:167], v[132:135]
	v_mfma_f32_16x16x32_bf16 v[132:135], v[80:83], v[160:163], v[136:139]
	v_mfma_f32_16x16x32_bf16 v[124:127], v[64:67], v[168:171], v[124:127]
	v_mfma_f32_16x16x32_bf16 v[120:123], v[80:83], v[168:171], v[120:123]
	v_mfma_f32_16x16x32_bf16 v[108:111], v[64:67], v[186:189], v[108:111]
	v_mfma_f32_16x16x32_bf16 v[104:107], v[80:83], v[186:189], v[104:107]
	v_mfma_f32_16x16x32_bf16 v[136:139], v[84:87], v[164:167], v[132:135]
	v_mfma_f32_16x16x32_bf16 v[124:127], v[68:71], v[172:175], v[124:127]
	v_mfma_f32_16x16x32_bf16 v[120:123], v[84:87], v[172:175], v[120:123]
	v_mfma_f32_16x16x32_bf16 v[108:111], v[68:71], v[194:197], v[108:111]
	v_mfma_f32_16x16x32_bf16 v[104:107], v[84:87], v[194:197], v[104:107]
	s_setprio 0
	s_barrier
	s_add_i32 s16, 0, 0x1c000
	v_add_u32_e32 v132, s16, v220
	s_add_i32 s10, s61, s21
	ds_read_b128 v[198:201], v132
	ds_read_b128 v[202:205], v132 offset:1024
	ds_read_b128 v[206:209], v132 offset:2048
	ds_read_b128 v[210:213], v132 offset:3072
	v_lshl_add_u64 v[132:133], v[214:215], 0, s[28:29]
	s_mov_b32 m0, s10
	s_nop 0
	global_load_lds_dwordx4 v[132:133], off
	v_lshl_add_u64 v[132:133], v[216:217], 0, s[28:29]
	s_add_i32 m0, s10, 0x2000
	s_nop 0
	global_load_lds_dwordx4 v[132:133], off
	s_barrier
	s_waitcnt lgkmcnt(0)
	s_setprio 1
	s_waitcnt lgkmcnt(0)
	v_mfma_f32_16x16x32_bf16 v[40:43], v[206:209], v[116:119], v[40:43]
	v_mfma_f32_16x16x32_bf16 v[132:135], v[198:201], v[116:119], v[148:151]
	v_mfma_f32_16x16x32_bf16 v[144:147], v[210:213], v[128:131], v[40:43]
	v_mfma_f32_16x16x32_bf16 v[40:43], v[198:201], v[160:163], v[44:47]
	v_mfma_f32_16x16x32_bf16 v[148:151], v[202:205], v[128:131], v[132:135]
	v_mfma_f32_16x16x32_bf16 v[132:135], v[202:205], v[164:167], v[40:43]
	v_mfma_f32_16x16x32_bf16 v[40:43], v[206:209], v[160:163], v[48:51]
	v_mfma_f32_16x16x32_bf16 v[128:131], v[210:213], v[164:167], v[40:43]
	v_mfma_f32_16x16x32_bf16 v[40:43], v[198:201], v[168:171], v[52:55]
	v_mfma_f32_16x16x32_bf16 v[116:119], v[202:205], v[172:175], v[40:43]
	v_mfma_f32_16x16x32_bf16 v[40:43], v[206:209], v[168:171], v[112:115]
	v_mfma_f32_16x16x32_bf16 v[112:115], v[210:213], v[172:175], v[40:43]
	v_mfma_f32_16x16x32_bf16 v[40:43], v[198:201], v[186:189], v[100:103]
	v_mfma_f32_16x16x32_bf16 v[100:103], v[202:205], v[194:197], v[40:43]
	v_mfma_f32_16x16x32_bf16 v[40:43], v[206:209], v[186:189], v[96:99]
	v_mfma_f32_16x16x32_bf16 v[96:99], v[210:213], v[194:197], v[40:43]
	s_setprio 0
	s_mov_b32 m0, s55
	v_lshl_add_u64 v[186:187], v[222:223], 0, s[28:29]
	s_barrier
	s_nop 2
	ds_read_b128 v[40:43], v221 offset:49152
	ds_read_b128 v[44:47], v221 offset:50176
	ds_read_b128 v[48:51], v221 offset:51200
	ds_read_b128 v[52:55], v221 offset:52224
	ds_read_b128 v[160:163], v221 offset:53248
	ds_read_b128 v[164:167], v221 offset:54272
	ds_read_b128 v[168:171], v221 offset:55296
	ds_read_b128 v[172:175], v221 offset:56320
	global_load_lds_dwordx4 v[186:187], off
	v_lshl_add_u64 v[186:187], v[224:225], 0, s[28:29]
	s_mov_b32 m0, s56
	s_nop 0
	global_load_lds_dwordx4 v[186:187], off
	s_barrier
; #define PG8_STAGE(bufoff, gbase, voff) do { _Pragma("unroll") for (int _i = 0; _i < 2; ++_i) \
;         __builtin_amdgcn_global_load_lds((const unsigned*)((const char*)(gbase) + (voff)[_i]), (LAS unsigned*)(lds + (bufoff) + ldsw + _i * 8192), 16, 0, 0); } while (0)
; #define PG8_WAIT_V(n) asm volatile("s_waitcnt vmcnt(" #n ")" ::: "memory")
; #define PG8_BAR __builtin_amdgcn_s_barrier()
; template <class Epi>
; __device__ __forceinline__ void gemm_phase(LAS unsigned char* lds, const Gemm g, const StaticOrder& S, const Epi& E) {
;     ...
;             PG8_BAR; PG8_WAIT_L(0); PG8_MMA(1, 0, At, B0); PG8_BAR; PG8_SCHED;
;             PG8_STAGE(PG8_SB(0, 1), b2 + hstep, voffB);
;             PG8_WAIT_V(6); PG8_BAR; PG8_MMA(1, 1, At, B1); PG8_BAR;
;             PG8_LDB(B0, 1, 0); PG8_SCHED; PG8_LDA(At, 1, 0); PG8_STAGE(PG8_SA(0, 1), a2 + hstep, voffA);
;             PG8_WAIT_L(8); PG8_BAR; PG8_WAIT_L(0); PG8_MMA(0, 0, At, B0); PG8_BAR; PG8_SCHED;
;             PG8_LDB(B1, 1, 1); PG8_STAGE(PG8_SB(1, 0), b3, voffB);
;             PG8_BAR; PG8_WAIT_L(0); PG8_MMA(0, 1, At, B1); PG8_BAR;
;             PG8_LDA(At, 1, 1); PG8_STAGE(PG8_SA(1, 0), a3, voffA);
;             PG8_BAR; PG8_WAIT_L(0); PG8_MMA(1, 0, At, B0); PG8_BAR; PG8_SCHED;
;             PG8_STAGE(PG8_SB(1, 1), b3 + hstep, voffB);
;             PG8_WAIT_V(6); PG8_BAR; PG8_MMA(1, 1, At, B1); PG8_BAR;
;         }
;     __device__ __forceinline__ void operator()(const f32x4 (&acc)[2][2][4][2], const Unit& u, int wr, int wc, int fr_, int fq_) const {
;     ...
;         const int lc = wc * 32 + fq * 8;
;         f32x4 gv[2][2], bv[2][2];
; #pragma unroll
;         for (int bj = 0; bj < 2; ++bj)
; #pragma unroll
;             for (int n = 0; n < 2; ++n) { const int col = u.pn * 256 + bj * 128 + lc + 4 * n; gv[bj][n] = *(const f32x4*)(g1 + col); bv[bj][n] = *(const f32x4*)(b1 + col); }
; #pragma unroll
;         for (int am = 0; am < 4; ++am) { const int ai = am >> 1, m0 = (am & 1) * 2;
;             u32x4 w[2][2]; float mu[2], rs[2];
; #pragma unroll
;             for (int mm = 0; mm < 2; ++mm) { const int m = mm; const int mg = m0 + mm;
;                 const int grow = u.pm * 256 + ai * 128 + mg * 16 + wr * 64 + fr;
; #pragma unroll
;                 for (int bj = 0; bj < 2; ++bj) w[m][bj] = *(const u32x4*)(Y1B + (size_t)grow * 1024 + u.pn * 256 + bj * 128 + lc);
;                 row_stats(st1, grow, fq, mu[m], rs[m]);
	s_waitcnt lgkmcnt(0)
	s_setprio 1
	s_waitcnt lgkmcnt(0)
	v_mfma_f32_16x16x32_bf16 v[92:95], v[64:67], v[40:43], v[92:95]
	v_mfma_f32_16x16x32_bf16 v[88:91], v[80:83], v[40:43], v[88:91]
	v_mfma_f32_16x16x32_bf16 v[76:79], v[64:67], v[48:51], v[76:79]
	v_mfma_f32_16x16x32_bf16 v[72:75], v[80:83], v[48:51], v[72:75]
	v_mfma_f32_16x16x32_bf16 v[60:63], v[64:67], v[160:163], v[60:63]
	v_mfma_f32_16x16x32_bf16 v[56:59], v[80:83], v[160:163], v[56:59]
	v_mfma_f32_16x16x32_bf16 v[12:15], v[64:67], v[168:171], v[12:15]
	v_mfma_f32_16x16x32_bf16 v[8:11], v[80:83], v[168:171], v[8:11]
	v_mfma_f32_16x16x32_bf16 v[92:95], v[68:71], v[44:47], v[92:95]
	v_mfma_f32_16x16x32_bf16 v[88:91], v[84:87], v[44:47], v[88:91]
	v_mfma_f32_16x16x32_bf16 v[76:79], v[68:71], v[52:55], v[76:79]
	v_mfma_f32_16x16x32_bf16 v[72:75], v[84:87], v[52:55], v[72:75]
	v_mfma_f32_16x16x32_bf16 v[60:63], v[68:71], v[164:167], v[60:63]
	v_mfma_f32_16x16x32_bf16 v[56:59], v[84:87], v[164:167], v[56:59]
	v_mfma_f32_16x16x32_bf16 v[12:15], v[68:71], v[172:175], v[12:15]
	v_mfma_f32_16x16x32_bf16 v[8:11], v[84:87], v[172:175], v[8:11]
	s_setprio 0
	s_barrier
	s_add_u32 s10, s14, 0xb0080
	s_addc_u32 s11, s15, 0
	s_add_i32 s14, s16, s21
	v_lshl_add_u64 v[64:65], s[10:11], 0, v[190:191]
	s_mov_b32 m0, s14
	s_nop 0
	global_load_lds_dwordx4 v[64:65], off
	v_lshl_add_u64 v[64:65], s[10:11], 0, v[176:177]
	s_add_i32 m0, s14, 0x2000
	s_nop 0
	global_load_lds_dwordx4 v[64:65], off
	s_waitcnt vmcnt(6)
	s_barrier
	s_setprio 1
	v_mfma_f32_16x16x32_bf16 v[24:27], v[198:201], v[40:43], v[24:27]
	v_mfma_f32_16x16x32_bf16 v[84:87], v[202:205], v[44:47], v[24:27]
	v_mfma_f32_16x16x32_bf16 v[24:27], v[206:209], v[40:43], v[28:31]
	v_mfma_f32_16x16x32_bf16 v[80:83], v[210:213], v[44:47], v[24:27]
	v_mfma_f32_16x16x32_bf16 v[24:27], v[198:201], v[48:51], v[32:35]
	v_mfma_f32_16x16x32_bf16 v[68:71], v[202:205], v[52:55], v[24:27]
	v_mfma_f32_16x16x32_bf16 v[24:27], v[206:209], v[48:51], v[36:39]
	v_mfma_f32_16x16x32_bf16 v[20:23], v[198:201], v[160:163], v[20:23]
	v_mfma_f32_16x16x32_bf16 v[16:19], v[206:209], v[160:163], v[16:19]
	v_mfma_f32_16x16x32_bf16 v[4:7], v[198:201], v[168:171], v[4:7]
	v_mfma_f32_16x16x32_bf16 v[0:3], v[206:209], v[168:171], v[0:3]
	v_mfma_f32_16x16x32_bf16 v[64:67], v[210:213], v[52:55], v[24:27]
	v_mfma_f32_16x16x32_bf16 v[20:23], v[202:205], v[164:167], v[20:23]
	v_mfma_f32_16x16x32_bf16 v[16:19], v[210:213], v[164:167], v[16:19]
	v_mfma_f32_16x16x32_bf16 v[4:7], v[202:205], v[172:175], v[4:7]
	v_mfma_f32_16x16x32_bf16 v[0:3], v[210:213], v[172:175], v[0:3]
	s_setprio 0
	s_add_i32 s53, s53, 2
	s_add_u32 s50, s50, 0x100
	s_addc_u32 s52, s52, 0
	s_cmp_gt_u32 s53, 41
	s_mov_b64 s[10:11], s[0:1]
	s_barrier
	s_cbranch_scc0 .LBB0_947
	s_lshl_b32 s0, s51, 8
	v_mov_b32_e32 v161, v218
	v_mov_b32_e32 v162, v219
	s_add_i32 s0, s0, s2
	s_lshl_b32 s50, s5, 8
	v_add_u32_e32 v188, s0, v161
	s_lshl_b32 s0, s5, 3
	v_lshlrev_b32_e32 v160, 3, v162
	s_ashr_i32 s51, s50, 31
	s_or_b32 s52, s0, s57
	v_add_u32_e32 v186, s54, v160
	s_ashr_i32 s53, s52, 31
	s_lshl_b64 s[10:11], s[50:51], 1
	v_ashrrev_i32_e32 v187, 31, v186
	v_xor_b32_e32 v163, 16, v231
	s_add_u32 s0, s36, s10
	v_cmp_lt_i32_e32 vcc, v163, v232
	s_addc_u32 s1, s37, s11
	v_lshlrev_b64 v[214:215], 1, v[186:187]
	v_add_u32_e32 v24, s50, v186
	v_cndmask_b32_e32 v163, v231, v163, vcc
	v_lshl_add_u64 v[200:201], s[0:1], 0, v[214:215]
	v_readlane_b32 s0, v253, 21
	v_ashrrev_i32_e32 v25, 31, v24
	v_ashrrev_i32_e32 v161, 31, v160
	v_lshlrev_b32_e32 v223, 2, v163
	v_xor_b32_e32 v163, 32, v231
	v_readlane_b32 s1, v253, 22
	v_ashrrev_i32_e32 v189, 31, v188
	v_lshlrev_b64 v[24:25], 2, v[24:25]
	v_cmp_lt_i32_e32 vcc, v163, v232
	v_lshl_add_u64 v[198:199], v[160:161], 2, s[0:1]
	v_lshlrev_b64 v[216:217], 11, v[188:189]
	v_lshlrev_b64 v[206:207], 7, v[188:189]
	v_lshl_add_u64 v[28:29], s[38:39], 0, v[24:25]
	v_lshl_add_u64 v[36:37], s[44:45], 0, v[24:25]
	v_cndmask_b32_e32 v163, v231, v163, vcc
	v_lshl_add_u64 v[160:161], v[200:201], 0, v[216:217]
	v_lshl_add_u64 v[164:165], v[198:199], 0, v[206:207]
	s_mov_b32 m0, 0x20000
	v_and_b32_e32 v196, 48, v231
	v_mov_b32_e32 v197, 0
	v_lshlrev_b32_e32 v196, 11, v196
	v_lshl_add_u64 v[210:211], v[160:161], 0, v[196:197]
	global_load_lds_dword v[210:211], off
	global_load_lds_dword v[210:211], off offset:256
	v_add_u32_e32 v196, 0x40000, v196
	v_lshl_add_u64 v[210:211], v[160:161], 0, v[196:197]
	global_load_lds_dword v[210:211], off
	global_load_lds_dword v[210:211], off offset:256
	v_and_b32_e32 v196, 48, v231
	v_lshlrev_b32_e32 v196, 7, v196
	v_lshl_add_u64 v[210:211], v[164:165], 0, v[196:197]
	global_load_lds_dword v[210:211], off
	v_add_u32_e32 v196, 0x4000, v196
	v_lshl_add_u64 v[210:211], v[164:165], 0, v[196:197]
	global_load_lds_dword v[210:211], off
	global_load_dwordx4 v[40:43], v[28:29], off offset:16
	global_load_dwordx4 v[48:51], v[28:29], off
	global_load_dwordx4 v[44:47], v[36:37], off offset:16
	global_load_dwordx4 v[52:55], v[36:37], off
	global_load_dwordx4 v[24:27], v[28:29], off offset:528
	global_load_dwordx4 v[32:35], v[28:29], off offset:512
	s_nop 0
	global_load_dwordx4 v[28:31], v[36:37], off offset:528
	s_nop 0
	global_load_dwordx4 v[36:39], v[36:37], off offset:512
	v_lshlrev_b32_e32 v222, 2, v163
	v_cmp_eq_u32_e32 vcc, 0, v162
	global_load_dwordx4 v[172:175], v[160:161], off
	global_load_dwordx4 v[168:171], v[160:161], off offset:256
	s_nop 0
	global_load_dwordx4 v[160:163], v[164:165], off offset:16
	s_nop 0
	global_load_dwordx4 v[164:167], v[164:165], off
	v_add_u32_e32 v194, 16, v188
	v_ashrrev_i32_e32 v195, 31, v194
	v_lshlrev_b64 v[204:205], 11, v[194:195]
	v_lshlrev_b64 v[202:203], 7, v[194:195]
	v_lshl_add_u64 v[208:209], v[198:199], 0, v[202:203]
	s_waitcnt vmcnt(0)
; __device__ __forceinline__ float lo_bf(unsigned x) { return __uint_as_float(x << 16); }
; __device__ __forceinline__ float hi_bf(unsigned x) { return __uint_as_float(x & 0xffff0000u); }
; __device__ __forceinline__ u32x4 pack8(const f32x4 a, const f32x4 b) { u32x4 w; w.x = cvt_pk_bf16(a[0], a[1]); w.y = cvt_pk_bf16(a[2], a[3]); w.z = cvt_pk_bf16(b[0], b[1]); w.w = cvt_pk_bf16(b[2], b[3]); return w; }
;     __device__ __forceinline__ void operator()(const f32x4 (&acc)[2][2][4][2], const Unit& u, int wr, int wc, int fr_, int fq_) const {
;     ...
;             for (int mm = 0; mm < 2; ++mm) { const int m = mm; const int mg = m0 + mm;
;                 const int grow = u.pm * 256 + ai * 128 + mg * 16 + wr * 64 + fr;
; #pragma unroll
;                 for (int bj = 0; bj < 2; ++bj) w[m][bj] = *(const u32x4*)(Y1B + (size_t)grow * 1024 + u.pn * 256 + bj * 128 + lc);
;                 row_stats(st1, grow, fq, mu[m], rs[m]);
;             }
;             asm volatile("" ::: "memory");
; #pragma unroll
;             for (int mm = 0; mm < 2; ++mm) { const int m = mm; const int mg = m0 + mm;
;                 const int grow = u.pm * 256 + ai * 128 + mg * 16 + wr * 64 + fr;
;                 float s = 0.f, ss = 0.f;
; #pragma unroll
;                 for (int bj = 0; bj < 2; ++bj) { const size_t off = (size_t)grow * 1024 + u.pn * 256 + bj * 128 + lc; const u32x4 ww = w[m][bj];
;                     f32x4 x0 = (f32x4){lo_bf(ww.x), hi_bf(ww.x), lo_bf(ww.y), hi_bf(ww.y)}, x1 = (f32x4){lo_bf(ww.z), hi_bf(ww.z), lo_bf(ww.w), hi_bf(ww.w)};
;                     x0 = (x0 - mu[m]) * rs[m] * gv[bj][0] + bv[bj][0]; x1 = (x1 - mu[m]) * rs[m] * gv[bj][1] + bv[bj][1];
;                     const f32x4 y0 = x0 * ALPHA + acc[ai][bj][mg][0], y1 = x1 * ALPHA + acc[ai][bj][mg][1];
;                     *(u32x4*)(XB + off) = pack8(y0, y1);
;                     s += (y0[0] + y0[1]) + (y0[2] + y0[3]) + (y1[0] + y1[1]) + (y1[2] + y1[3]);
;                     ss += (y0[0] * y0[0] + y0[1] * y0[1]) + (y0[2] * y0[2] + y0[3] * y0[3]) + (y1[0] * y1[0] + y1[1] * y1[1]) + (y1[2] * y1[2] + y1[3] * y1[3]);
;                 }
;                 s += __shfl_xor(s, 16); s += __shfl_xor(s, 32); ss += __shfl_xor(ss, 16); ss += __shfl_xor(ss, 32);
;                 if (fq == 0) { f32x2_t o2 = {s, ss}; *(f32x2_t*)(st2 + (size_t)grow * 32 + (u.pn * 4 + wc) * 2) = o2; }
	v_lshlrev_b32_e32 v189, 16, v172
	v_pk_add_f32 v[160:161], v[160:161], v[162:163]
	v_pk_add_f32 v[164:165], v[164:165], v[166:167]
	v_and_b32_e32 v172, 0xffff0000, v172
	v_pk_add_f32 v[160:161], v[164:165], v[160:161]
	ds_bpermute_b32 v162, v223, v160
	ds_bpermute_b32 v163, v223, v161
	v_and_b32_e32 v224, 0xffff0000, v175
	s_waitcnt lgkmcnt(0)
	v_pk_add_f32 v[160:161], v[160:161], v[162:163]
	ds_bpermute_b32 v162, v222, v160
	ds_bpermute_b32 v163, v222, v161
	s_waitcnt lgkmcnt(0)
	v_pk_add_f32 v[160:161], v[160:161], v[162:163]
	s_nop 0
	v_pk_mul_f32 v[212:213], v[160:161], s[74:75] op_sel_hi:[1,0]
	s_nop 0
	v_fma_f32 v160, -v212, v212, v213
	v_max_f32_e32 v160, 0, v160
	v_add_f32_e32 v160, 0x3727c5ac, v160
	v_cmp_gt_f32_e64 s[0:1], s75, v160
	v_mul_f32_e32 v161, 0x4b800000, v160
	v_lshlrev_b32_e32 v213, 16, v175
	v_cndmask_b32_e64 v160, v160, v161, s[0:1]
	v_rsq_f32_e32 v160, v160
	s_nop 0
	v_mul_f32_e32 v161, 0x45800000, v160
	v_cndmask_b32_e64 v192, v160, v161, s[0:1]
	v_lshl_add_u64 v[160:161], v[200:201], 0, v[204:205]
	global_load_dwordx4 v[164:167], v[160:161], off
	s_nop 0
	global_load_dwordx4 v[160:163], v[160:161], off offset:256
	s_nop 0
	global_load_dwordx4 v[194:197], v[208:209], off offset:16
	s_nop 0
	global_load_dwordx4 v[208:211], v[208:209], off
	s_waitcnt vmcnt(1)
	v_pk_add_f32 v[194:195], v[194:195], v[196:197]
	s_waitcnt vmcnt(0)
	v_pk_add_f32 v[208:209], v[208:209], v[210:211]
	s_nop 0
	v_pk_add_f32 v[194:195], v[208:209], v[194:195]
	ds_bpermute_b32 v196, v223, v194
	ds_bpermute_b32 v197, v223, v195
	s_waitcnt lgkmcnt(0)
	v_pk_add_f32 v[208:209], v[194:195], v[196:197]
	v_lshlrev_b32_e32 v194, 16, v173
	v_and_b32_e32 v195, 0xffff0000, v173
	v_lshlrev_b32_e32 v196, 16, v174
	v_and_b32_e32 v197, 0xffff0000, v174
	v_sub_f32_e32 v175, v195, v212
	v_sub_f32_e32 v174, v194, v212
	v_sub_f32_e32 v195, v197, v212
	v_sub_f32_e32 v194, v196, v212
	v_sub_f32_e32 v173, v172, v212
	v_sub_f32_e32 v172, v189, v212
	v_pk_mul_f32 v[174:175], v[174:175], v[192:193] op_sel_hi:[1,0]
	v_sub_f32_e32 v197, v224, v212
	v_sub_f32_e32 v196, v213, v212
	v_pk_mul_f32 v[194:195], v[194:195], v[192:193] op_sel_hi:[1,0]
	v_pk_mul_f32 v[172:173], v[172:173], v[192:193] op_sel_hi:[1,0]
	v_pk_fma_f32 v[174:175], v[50:51], v[174:175], v[54:55]
	v_pk_mul_f32 v[196:197], v[196:197], v[192:193] op_sel_hi:[1,0]
	v_pk_fma_f32 v[194:195], v[40:41], v[194:195], v[44:45]
	v_pk_fma_f32 v[172:173], v[48:49], v[172:173], v[52:53]
	v_pk_fma_f32 v[196:197], v[42:43], v[196:197], v[46:47]
	v_pk_fma_f32 v[158:159], v[174:175], s[22:23], v[158:159] op_sel_hi:[1,0,1]
	v_pk_fma_f32 v[174:175], v[194:195], s[22:23], v[152:153] op_sel_hi:[1,0,1]
	v_lshl_add_u64 v[194:195], s[46:47], 0, v[216:217]
	v_pk_fma_f32 v[156:157], v[172:173], s[22:23], v[156:157] op_sel_hi:[1,0,1]
	v_pk_fma_f32 v[172:173], v[196:197], s[22:23], v[154:155] op_sel_hi:[1,0,1]
	v_lshl_add_u64 v[194:195], v[194:195], 0, s[10:11]
	v_cvt_pk_bf16_f32 v152, v156, v157
	v_cvt_pk_bf16_f32 v153, v158, v159
	v_cvt_pk_bf16_f32 v154, v174, v175
	v_cvt_pk_bf16_f32 v155, v172, v173
	v_lshl_add_u64 v[194:195], v[194:195], 0, v[214:215]
	global_store_dwordx4 v[194:195], v[152:155], off
	v_and_b32_e32 v189, 0xffff0000, v169
	v_lshlrev_b32_e32 v214, 16, v171
	v_pk_mov_b32 v[152:153], v[156:157], v[158:159] op_sel:[1,0]
	v_mov_b32_e32 v154, v156
	v_mov_b32_e32 v155, v159
	v_pk_mul_f32 v[158:159], v[158:159], v[158:159]
	v_pk_mul_f32 v[156:157], v[156:157], v[156:157]
	v_pk_add_f32 v[152:153], v[152:153], v[154:155]
	v_pk_mov_b32 v[196:197], v[156:157], v[158:159] op_sel:[1,0]
	v_mov_b32_e32 v157, v159
	v_pk_add_f32 v[156:157], v[196:197], v[156:157]
	v_add_f32_e32 v154, v174, v175
	v_pk_add_f32 v[156:157], v[156:157], v[156:157] op_sel_hi:[0,1]
	v_mul_f32_e32 v156, v174, v174
	v_pk_fma_f32 v[158:159], v[174:175], v[174:175], v[156:157] op_sel_hi:[1,1,0]
	v_lshlrev_b32_e32 v155, 16, v168
	v_and_b32_e32 v158, 0xffff0000, v168
	v_lshlrev_b32_e32 v174, 16, v169
	v_lshlrev_b32_e32 v196, 16, v170
	v_and_b32_e32 v197, 0xffff0000, v170
	v_and_b32_e32 v213, 0xffff0000, v171
	v_sub_f32_e32 v169, v158, v212
	v_sub_f32_e32 v168, v155, v212
	v_sub_f32_e32 v171, v189, v212
	v_sub_f32_e32 v170, v174, v212
	v_sub_f32_e32 v197, v197, v212
	v_sub_f32_e32 v196, v196, v212
	v_sub_f32_e32 v213, v213, v212
	v_sub_f32_e32 v212, v214, v212
	v_pk_mul_f32 v[170:171], v[170:171], v[192:193] op_sel_hi:[1,0]
	v_pk_mul_f32 v[168:169], v[168:169], v[192:193] op_sel_hi:[1,0]
	v_pk_mul_f32 v[212:213], v[212:213], v[192:193] op_sel_hi:[1,0]
	v_pk_mul_f32 v[196:197], v[196:197], v[192:193] op_sel_hi:[1,0]
	v_pk_fma_f32 v[168:169], v[32:33], v[168:169], v[36:37]
	v_pk_fma_f32 v[170:171], v[34:35], v[170:171], v[38:39]
	v_pk_fma_f32 v[196:197], v[24:25], v[196:197], v[28:29]
	v_pk_fma_f32 v[212:213], v[26:27], v[212:213], v[30:31]
	v_pk_fma_f32 v[150:151], v[170:171], s[22:23], v[150:151] op_sel_hi:[1,0,1]
	v_pk_fma_f32 v[148:149], v[168:169], s[22:23], v[148:149] op_sel_hi:[1,0,1]
	v_pk_fma_f32 v[168:169], v[212:213], s[22:23], v[146:147] op_sel_hi:[1,0,1]
	v_pk_fma_f32 v[170:171], v[196:197], s[22:23], v[144:145] op_sel_hi:[1,0,1]
	v_cvt_pk_bf16_f32 v144, v148, v149
	v_cvt_pk_bf16_f32 v145, v150, v151
	v_cvt_pk_bf16_f32 v146, v170, v171
	v_cvt_pk_bf16_f32 v147, v168, v169
	global_store_dwordx4 v[194:195], v[144:147], off offset:256
	v_add_f32_e32 v174, v170, v171
	v_mul_f32_e32 v155, v170, v170
	v_pk_mov_b32 v[144:145], v[148:149], v[150:151] op_sel:[1,0]
	v_mov_b32_e32 v146, v148
	v_mov_b32_e32 v147, v151
	v_pk_add_f32 v[144:145], v[144:145], v[146:147]
	v_mul_f32_e32 v146, v148, v148
	v_pk_fma_f32 v[146:147], v[148:149], v[148:149], v[146:147] op_sel_hi:[1,1,0]
	v_mul_f32_e32 v170, v171, v171
	v_mul_f32_e32 v146, v150, v150
	v_pk_fma_f32 v[148:149], v[150:151], v[150:151], v[146:147] op_sel_hi:[1,1,0]
	v_mul_f32_e32 v146, v168, v168
	v_pk_fma_f32 v[150:151], v[168:169], v[168:169], v[146:147] op_sel_hi:[1,1,0]
	v_mov_b32_e32 v146, v172
	v_mov_b32_e32 v148, v173
	v_pk_add_f32 v[146:147], v[146:147], v[148:149]
	v_pk_add_f32 v[148:149], v[152:153], v[152:153] op_sel:[0,1] op_sel_hi:[1,0]
	v_mul_f32_e32 v156, v173, v173
	v_pk_add_f32 v[144:145], v[144:145], v[144:145] op_sel:[0,1] op_sel_hi:[1,0]
	v_mov_b32_e32 v149, v170
	v_mul_f32_e32 v175, v172, v172
	v_mov_b32_e32 v145, v156
	v_mov_b32_e32 v158, v168
	v_mov_b32_e32 v156, v169
	v_pk_add_f32 v[148:149], v[154:155], v[148:149]
	v_pk_add_f32 v[144:145], v[174:175], v[144:145]
	v_pk_add_f32 v[156:157], v[158:159], v[156:157]
	v_pk_add_f32 v[146:147], v[148:149], v[146:147]
	v_mov_b32_e32 v150, v191
	v_pk_add_f32 v[144:145], v[144:145], v[156:157]
	v_pk_add_f32 v[146:147], v[146:147], v[150:151]
	ds_bpermute_b32 v210, v222, v208
	v_pk_add_f32 v[144:145], v[144:145], v[146:147]
	ds_bpermute_b32 v146, v223, v144
	ds_bpermute_b32 v147, v223, v145
	ds_bpermute_b32 v211, v222, v209
	s_waitcnt lgkmcnt(1)
	v_pk_add_f32 v[144:145], v[144:145], v[146:147]
	ds_bpermute_b32 v146, v222, v144
	ds_bpermute_b32 v147, v222, v145
	s_and_saveexec_b64 s[0:1], vcc
	s_cbranch_execz .LBB0_950
;     __device__ __forceinline__ void operator()(const f32x4 (&acc)[2][2][4][2], const Unit& u, int wr, int wc, int fr_, int fq_) const {
;     ...
;                 s += __shfl_xor(s, 16); s += __shfl_xor(s, 32); ss += __shfl_xor(ss, 16); ss += __shfl_xor(ss, 32);
;                 if (fq == 0) { f32x2_t o2 = {s, ss}; *(f32x2_t*)(st2 + (size_t)grow * 32 + (u.pn * 4 + wc) * 2) = o2; }
;             }
	v_lshl_add_u64 v[148:149], s[8:9], 0, v[206:207]
	v_lshl_add_u64 v[148:149], s[52:53], 2, v[148:149]
	s_waitcnt lgkmcnt(0)
	v_pk_add_f32 v[144:145], v[144:145], v[146:147]
	global_store_dwordx2 v[148:149], v[144:145], off

; #define LAS __attribute__((address_space(3)))
; __global__ void __launch_bounds__(512) fwd_megakernel(Params p) {
;     extern __shared__ __attribute__((aligned(16))) unsigned char lds_raw[];
;     LAS unsigned char* lds = (LAS unsigned char*)lds_raw;
	.amdhsa_kernel _Z14fwd_megakernel6Params
		.amdhsa_group_segment_fixed_size 0
		.amdhsa_private_segment_fixed_size 0
		.amdhsa_kernarg_size 384
		.amdhsa_user_sgpr_count 2
		.amdhsa_user_sgpr_dispatch_ptr 0
		.amdhsa_user_sgpr_queue_ptr 0
		.amdhsa_user_sgpr_kernarg_segment_ptr 1
		.amdhsa_user_sgpr_dispatch_id 0
		.amdhsa_user_sgpr_kernarg_preload_length 0
		.amdhsa_user_sgpr_kernarg_preload_offset 0
		.amdhsa_user_sgpr_private_segment_size 0
		.amdhsa_uses_dynamic_stack 0
		.amdhsa_enable_private_segment 0
		.amdhsa_system_sgpr_workgroup_id_x 1
		.amdhsa_system_sgpr_workgroup_id_y 0
		.amdhsa_system_sgpr_workgroup_id_z 0
		.amdhsa_system_sgpr_workgroup_info 0
		.amdhsa_system_vgpr_workitem_id 2
		.amdhsa_next_free_vgpr 256
		.amdhsa_next_free_sgpr 100
		.amdhsa_accum_offset 256
		.amdhsa_reserve_vcc 1
		.amdhsa_float_round_mode_32 0
		.amdhsa_float_round_mode_16_64 0
		.amdhsa_float_denorm_mode_32 3
		.amdhsa_float_denorm_mode_16_64 3
		.amdhsa_dx10_clamp 1
		.amdhsa_ieee_mode 1
		.amdhsa_fp16_overflow 0
		.amdhsa_tg_split 0
		.amdhsa_exception_fp_ieee_invalid_op 0
		.amdhsa_exception_fp_denorm_src 0
		.amdhsa_exception_fp_ieee_div_zero 0
		.amdhsa_exception_fp_ieee_overflow 0
		.amdhsa_exception_fp_ieee_underflow 0
		.amdhsa_exception_fp_ieee_inexact 0
		.amdhsa_exception_int_div_zero 0
	.end_amdhsa_kernel

; #define LAS __attribute__((address_space(3)))
; __global__ void __launch_bounds__(512) fwd_megakernel(Params p) {
;     extern __shared__ __attribute__((aligned(16))) unsigned char lds_raw[];
;     LAS unsigned char* lds = (LAS unsigned char*)lds_raw;
amdhsa.kernels:
  - .agpr_count:     0
    .args:
      - .offset:         0
        .size:           128
        .value_kind:     by_value
      - .offset:         128
        .size:           4
        .value_kind:     hidden_block_count_x
      - .offset:         132
        .size:           4
        .value_kind:     hidden_block_count_y
      - .offset:         136
        .size:           4
        .value_kind:     hidden_block_count_z
      - .offset:         140
        .size:           2
        .value_kind:     hidden_group_size_x
      - .offset:         142
        .size:           2
        .value_kind:     hidden_group_size_y
      - .offset:         144
        .size:           2
        .value_kind:     hidden_group_size_z
      - .offset:         146
        .size:           2
        .value_kind:     hidden_remainder_x
      - .offset:         148
        .size:           2
        .value_kind:     hidden_remainder_y
      - .offset:         150
        .size:           2
        .value_kind:     hidden_remainder_z
      - .offset:         168
        .size:           8
        .value_kind:     hidden_global_offset_x
      - .offset:         176
        .size:           8
        .value_kind:     hidden_global_offset_y
      - .offset:         184
        .size:           8
        .value_kind:     hidden_global_offset_z
      - .offset:         192
        .size:           2
        .value_kind:     hidden_grid_dims
      - .offset:         216
        .size:           8
        .value_kind:     hidden_multigrid_sync_arg
      - .offset:         248
        .size:           4
        .value_kind:     hidden_dynamic_lds_size
    .group_segment_fixed_size: 0
    .kernarg_segment_align: 8
    .kernarg_segment_size: 384
    .language:       OpenCL C
    .language_version:
      - 2
      - 0
    .max_flat_workgroup_size: 512
    .name:           _Z14fwd_megakernel6Params
    .private_segment_fixed_size: 0
    .sgpr_count:     106
    .sgpr_spill_count: 274
    .symbol:         _Z14fwd_megakernel6Params.kd
    .uniform_work_group_size: 1
    .uses_dynamic_stack: false
    .vgpr_count:     256
    .vgpr_spill_count: 0
    .wavefront_size: 64
